# attention prologue reordered (state init under the load latency, tile 0 written to LDS and tile 1 loads issued before the rope math), plus the first-tile rescale skip; hot loop unchanged at the same a
# speedup vs baseline: 1.0084x; 1.0042x over previous
; #define SLOAD(i, k0) do { sr_[i].a0 = *reinterpret_cast<const bf16x8*>(&KVh[(size_t)((k0) + sr) * NKV + c16 * 8]); sr_[i].a1 = *reinterpret_cast<const bf16x8*>(&KVh[(size_t)((k0) + 32 + sr) * NKV + c16 * 8]); \
;     sr_[i].rr = *reinterpret_cast<const bf16x8*>(&KR[(size_t)((k0) + rkey) * 32 + rch * 8]); } while (0)
; #define SWRITE(b, i) do { if (isK) { *(bf16x8*)(K_lds + (b) * SHM_K + kst0) = sr_[i].a0; *(bf16x8*)(K_lds + (b) * SHM_K + kst1) = sr_[i].a1; } \
;     else { *(bf16x8*)(V_lds + (b) * SHM_V + vst0) = sr_[i].a0; *(bf16x8*)(V_lds + (b) * SHM_V + vst1) = sr_[i].a1; } \
;     if (rwr) *(bf16x8*)(K_lds + (b) * SHM_K + rst) = sr_[i].rr; } while (0)
; #define SWAIT() asm volatile("s_waitcnt vmcnt(3)" ::: "memory")
; __device__ __forceinline__ void attn_body(const bf16_t* __restrict__ Qb, const bf16_t* __restrict__ KVh, const bf16_t* __restrict__ KR, const float* __restrict__ ropeq,
;                                           bf16_t* __restrict__ Ob, int seq, char* lds, const int tid) {
;     ...
;     { const bf16_t* Qw = Qb + (size_t)(wid * QBLK + r32) * NQ + hi * 8;
; #pragma unroll
;       for (int d0 = 0; d0 < 4; ++d0) qr[d0] = *reinterpret_cast<const bf16x8*>(Qw + d0 * 16);
;       const u32x4 w1 = *reinterpret_cast<const u32x4*>(Qw + 64), w2 = *reinterpret_cast<const u32x4*>(Qw + 80);
;       float x1[8], x2[8]; unpack8(w1, x1); unpack8(w2, x2);
;       const float* rp = ropeq + (size_t)(wid * QBLK + r32) * 32 + hi * 8;
;     ...
;     SLOAD(SE, 0); asm volatile("s_waitcnt vmcnt(0)" ::: "memory"); SWRITE(0, SE); __syncthreads();
;     qkt(pA0, pA1, K_lds, qr, r32, hi); partialSM(pA0, pA1, m_reg, mnA, alA);
;     SLOAD(SO, KVBLK); if (2 < NT) SLOAD(SE, 2 * KVBLK);
;     SWAIT(); SWRITE(1, SO); __syncthreads();
.LA_item:
	s_and_b32 s21, s20, 7
	s_lshr_b32 s10, s20, 3
	s_and_b32 s10, s10, 15
	s_lshr_b32 s11, s20, 7
	s_lshl_b32 s12, s11, 12
	s_lshl_b32 s13, s21, 9
	s_add_u32 s12, s12, s13
	s_lshl_b32 s13, s23, 6
	s_add_u32 s12, s12, s13
	s_mul_i32 s14, s12, 0xc00
	s_mul_i32 s15, s10, 0xc0
	s_add_u32 s14, s14, s15
	s_add_u32 s14, s14, 0xac00000
	s_add_u32 s30, s26, s14
	s_addc_u32 s31, s27, 0
	s_lshl_b32 s14, s12, 7
	s_add_u32 s14, s14, 0x100000
	s_add_u32 s40, s26, s14
	s_addc_u32 s41, s27, 0
	s_lshl_b32 s14, s12, 11
	s_lshl_b32 s15, s10, 7
	s_add_u32 s14, s14, s15
	s_add_u32 s14, s14, 0x6c00000
	s_add_u32 s42, s26, s14
	s_addc_u32 s43, s27, 0
	s_lshl_b32 s14, s11, 24
	s_lshl_b32 s15, s10, 8
	s_add_u32 s14, s14, s15
	s_add_u32 s14, s14, 0x10c00000
	s_add_u32 s28, s26, s14
	s_addc_u32 s29, s27, 0
	s_lshl_b32 s14, s11, 18
	s_add_u32 s14, s14, 0x1d400000
	s_add_u32 s44, s26, s14
	s_addc_u32 s45, s27, 0
	s_barrier
	v_add_u32_e32 v247, 0x20000, v243
	global_load_dwordx4 v[228:231], v243, s[28:29]
	global_load_dwordx4 v[130:133], v247, s[28:29]
	global_load_dwordx4 v[248:251], v244, s[44:45]
	s_add_u32 s28, s28, 0x40000
	s_addc_u32 s29, s29, 0
	s_add_u32 s44, s44, 0x1000
	s_addc_u32 s45, s45, 0
	v_and_b32_e32 v245, 31, v211
	v_lshrrev_b32_e32 v246, 5, v211
	v_mul_u32_u24_e32 v247, 0xc00, v245
	v_lshl_add_u32 v247, v246, 4, v247
	v_lshlrev_b32_e32 v202, 7, v245
	v_lshl_add_u32 v202, v246, 5, v202
	global_load_dwordx4 v[142:145], v247, s[30:31] offset:0
	global_load_dwordx4 v[146:149], v247, s[30:31] offset:32
	global_load_dwordx4 v[150:153], v247, s[30:31] offset:64
	global_load_dwordx4 v[154:157], v247, s[30:31] offset:96
	global_load_dwordx4 v[158:161], v247, s[30:31] offset:128
	global_load_dwordx4 v[162:165], v247, s[30:31] offset:160
	global_load_dwordx4 v[66:69], v202, s[40:41] offset:0
	global_load_dwordx4 v[70:73], v202, s[40:41] offset:16
	global_load_dwordx4 v[74:77], v202, s[40:41] offset:64
	global_load_dwordx4 v[78:81], v202, s[40:41] offset:80
	v_add_u32_e32 v247, 0x18000, v247
	v_add_u32_e32 v202, 0x1000, v202
	global_load_dwordx4 v[166:169], v247, s[30:31] offset:0
	global_load_dwordx4 v[170:173], v247, s[30:31] offset:32
	global_load_dwordx4 v[174:177], v247, s[30:31] offset:64
	global_load_dwordx4 v[178:181], v247, s[30:31] offset:96
	global_load_dwordx4 v[182:185], v247, s[30:31] offset:128
	global_load_dwordx4 v[186:189], v247, s[30:31] offset:160
	global_load_dwordx4 v[98:101], v202, s[40:41] offset:0
	global_load_dwordx4 v[102:105], v202, s[40:41] offset:16
	global_load_dwordx4 v[106:109], v202, s[40:41] offset:64
	global_load_dwordx4 v[110:113], v202, s[40:41] offset:80
	v_mov_b32_e32 v141, 0xf149f2ca
	v_mov_b32_e32 v254, 0
	v_mov_b32_e32 v64, 0
	v_mov_b32_e32 v0, 0
	v_mov_b32_e32 v1, 0
	v_mov_b32_e32 v2, 0
	v_mov_b32_e32 v3, 0
	v_mov_b32_e32 v4, 0
	v_mov_b32_e32 v5, 0
	v_mov_b32_e32 v6, 0
	v_mov_b32_e32 v7, 0
	v_mov_b32_e32 v8, 0
	v_mov_b32_e32 v9, 0
	v_mov_b32_e32 v10, 0
	v_mov_b32_e32 v11, 0
	v_mov_b32_e32 v12, 0
	v_mov_b32_e32 v13, 0
	v_mov_b32_e32 v14, 0
	v_mov_b32_e32 v15, 0
	v_mov_b32_e32 v16, 0
	v_mov_b32_e32 v17, 0
	v_mov_b32_e32 v18, 0
	v_mov_b32_e32 v19, 0
	v_mov_b32_e32 v20, 0
	v_mov_b32_e32 v21, 0
	v_mov_b32_e32 v22, 0
	v_mov_b32_e32 v23, 0
	v_mov_b32_e32 v24, 0
	v_mov_b32_e32 v25, 0
	v_mov_b32_e32 v26, 0
	v_mov_b32_e32 v27, 0
	v_mov_b32_e32 v28, 0
	v_mov_b32_e32 v29, 0
	v_mov_b32_e32 v30, 0
	v_mov_b32_e32 v31, 0
	v_mov_b32_e32 v139, 0xf149f2ca
	v_mov_b32_e32 v255, 0
	v_mov_b32_e32 v134, 0
	v_mov_b32_e32 v32, 0
	v_mov_b32_e32 v33, 0
	v_mov_b32_e32 v34, 0
	v_mov_b32_e32 v35, 0
	v_mov_b32_e32 v36, 0
	v_mov_b32_e32 v37, 0
	v_mov_b32_e32 v38, 0
	v_mov_b32_e32 v39, 0
	v_mov_b32_e32 v40, 0
	v_mov_b32_e32 v41, 0
	v_mov_b32_e32 v42, 0
	v_mov_b32_e32 v43, 0
	v_mov_b32_e32 v44, 0
	v_mov_b32_e32 v45, 0
	v_mov_b32_e32 v46, 0
	v_mov_b32_e32 v47, 0
	v_mov_b32_e32 v48, 0
	v_mov_b32_e32 v49, 0
	v_mov_b32_e32 v50, 0
	v_mov_b32_e32 v51, 0
	v_mov_b32_e32 v52, 0
	v_mov_b32_e32 v53, 0
	v_mov_b32_e32 v54, 0
	v_mov_b32_e32 v55, 0
	v_mov_b32_e32 v56, 0
	v_mov_b32_e32 v57, 0
	v_mov_b32_e32 v58, 0
	v_mov_b32_e32 v59, 0
	v_mov_b32_e32 v60, 0
	v_mov_b32_e32 v61, 0
	v_mov_b32_e32 v62, 0
	v_mov_b32_e32 v63, 0
	s_waitcnt vmcnt(0)
	s_mov_b32 s18, 0
	s_mov_b32 s19, 0x4000
	s_mov_b32 s22, 0x8000
	s_mov_b32 s16, 0
	s_waitcnt vmcnt(0)
	v_add_u32_e32 v246, s18, v240
	v_add_u32_e32 v245, s18, v241
	ds_write_b128 v246, v[228:231]
	ds_write_b128 v245, v[130:133]
	s_cmp_eq_u64 s[2:3], 0
	s_cbranch_scc1 .LA_swp
	v_add_u32_e32 v245, s18, v242
	ds_write_b128 v245, v[248:251] offset:49152
; __device__ __forceinline__ unsigned pk2(float lo, float hi) { return f2bf(lo) | (f2bf(hi) << 16); }
; #define SLOAD(i, k0) do { sr_[i].a0 = *reinterpret_cast<const bf16x8*>(&KVh[(size_t)((k0) + sr) * NKV + c16 * 8]); sr_[i].a1 = *reinterpret_cast<const bf16x8*>(&KVh[(size_t)((k0) + 32 + sr) * NKV + c16 * 8]); \
;     sr_[i].rr = *reinterpret_cast<const bf16x8*>(&KR[(size_t)((k0) + rkey) * 32 + rch * 8]); } while (0)
; #define SWRITE(b, i) do { if (isK) { *(bf16x8*)(K_lds + (b) * SHM_K + kst0) = sr_[i].a0; *(bf16x8*)(K_lds + (b) * SHM_K + kst1) = sr_[i].a1; } \
;     else { *(bf16x8*)(V_lds + (b) * SHM_V + vst0) = sr_[i].a0; *(bf16x8*)(V_lds + (b) * SHM_V + vst1) = sr_[i].a1; } \
;     if (rwr) *(bf16x8*)(K_lds + (b) * SHM_K + rst) = sr_[i].rr; } while (0)
; #define SWAIT() asm volatile("s_waitcnt vmcnt(3)" ::: "memory")
; __device__ __forceinline__ void attn_body(const bf16_t* __restrict__ Qb, const bf16_t* __restrict__ KVh, const bf16_t* __restrict__ KR, const float* __restrict__ ropeq,
;                                           bf16_t* __restrict__ Ob, int seq, char* lds, const int tid) {
;     ...
;       float y1[8], y2[8];
; #pragma unroll
;       for (int e = 0; e < 8; ++e) { const float c = rp[e], s = rp[16 + e]; y1[e] = x1[e] * c - x2[e] * s; y2[e] = x1[e] * s + x2[e] * c; }
;       u32x4 o1 = {pk2(y1[0], y1[1]), pk2(y1[2], y1[3]), pk2(y1[4], y1[5]), pk2(y1[6], y1[7])};
;       u32x4 o2 = {pk2(y2[0], y2[1]), pk2(y2[2], y2[3]), pk2(y2[4], y2[5]), pk2(y2[6], y2[7])};
;       qr[4] = *reinterpret_cast<bf16x8*>(&o1); qr[5] = *reinterpret_cast<bf16x8*>(&o2); }
;     ...
;     SLOAD(SO, KVBLK); if (2 < NT) SLOAD(SE, 2 * KVBLK);
;     SWAIT(); SWRITE(1, SO); __syncthreads();
.LA_swp:
	v_add_u32_e32 v247, 0x20000, v243
	global_load_dwordx4 v[228:231], v243, s[28:29]
	global_load_dwordx4 v[130:133], v247, s[28:29]
	global_load_dwordx4 v[248:251], v244, s[44:45]
	s_add_u32 s28, s28, 0x40000
	s_addc_u32 s29, s29, 0
	s_add_u32 s44, s44, 0x1000
	s_addc_u32 s45, s45, 0
	v_lshlrev_b32_e32 v82, 16, v158
	v_lshlrev_b32_e32 v83, 16, v162
	v_mul_f32_e32 v84, v83, v74
	v_fma_f32 v86, v82, v66, -v84
	v_mul_f32_e32 v84, v83, v66
	v_fma_f32 v87, v82, v74, v84
	v_and_b32_e32 v82, 0xffff0000, v158
	v_and_b32_e32 v83, 0xffff0000, v162
	v_mul_f32_e32 v84, v83, v75
	v_fma_f32 v85, v82, v67, -v84
	v_cvt_pk_bf16_f32 v158, v86, v85
	v_mul_f32_e32 v84, v83, v67
	v_fma_f32 v85, v82, v75, v84
	v_cvt_pk_bf16_f32 v162, v87, v85
	v_lshlrev_b32_e32 v82, 16, v159
	v_lshlrev_b32_e32 v83, 16, v163
	v_mul_f32_e32 v84, v83, v76
	v_fma_f32 v86, v82, v68, -v84
	v_mul_f32_e32 v84, v83, v68
	v_fma_f32 v87, v82, v76, v84
	v_and_b32_e32 v82, 0xffff0000, v159
	v_and_b32_e32 v83, 0xffff0000, v163
	v_mul_f32_e32 v84, v83, v77
	v_fma_f32 v85, v82, v69, -v84
	v_cvt_pk_bf16_f32 v159, v86, v85
	v_mul_f32_e32 v84, v83, v69
	v_fma_f32 v85, v82, v77, v84
	v_cvt_pk_bf16_f32 v163, v87, v85
	v_lshlrev_b32_e32 v82, 16, v160
	v_lshlrev_b32_e32 v83, 16, v164
	v_mul_f32_e32 v84, v83, v78
	v_fma_f32 v86, v82, v70, -v84
	v_mul_f32_e32 v84, v83, v70
	v_fma_f32 v87, v82, v78, v84
	v_and_b32_e32 v82, 0xffff0000, v160
	v_and_b32_e32 v83, 0xffff0000, v164
	v_mul_f32_e32 v84, v83, v79
	v_fma_f32 v85, v82, v71, -v84
	v_cvt_pk_bf16_f32 v160, v86, v85
	v_mul_f32_e32 v84, v83, v71
	v_fma_f32 v85, v82, v79, v84
	v_cvt_pk_bf16_f32 v164, v87, v85
	v_lshlrev_b32_e32 v82, 16, v161
	v_lshlrev_b32_e32 v83, 16, v165
	v_mul_f32_e32 v84, v83, v80
	v_fma_f32 v86, v82, v72, -v84
	v_mul_f32_e32 v84, v83, v72
	v_fma_f32 v87, v82, v80, v84
	v_and_b32_e32 v82, 0xffff0000, v161
	v_and_b32_e32 v83, 0xffff0000, v165
	v_mul_f32_e32 v84, v83, v81
	v_fma_f32 v85, v82, v73, -v84
	v_cvt_pk_bf16_f32 v161, v86, v85
	v_mul_f32_e32 v84, v83, v73
	v_fma_f32 v85, v82, v81, v84
	v_cvt_pk_bf16_f32 v165, v87, v85
	v_lshlrev_b32_e32 v114, 16, v182
	v_lshlrev_b32_e32 v115, 16, v186
	v_mul_f32_e32 v116, v115, v106
	v_fma_f32 v118, v114, v98, -v116
	v_mul_f32_e32 v116, v115, v98
	v_fma_f32 v119, v114, v106, v116
	v_and_b32_e32 v114, 0xffff0000, v182
	v_and_b32_e32 v115, 0xffff0000, v186
	v_mul_f32_e32 v116, v115, v107
	v_fma_f32 v117, v114, v99, -v116
	v_cvt_pk_bf16_f32 v182, v118, v117
	v_mul_f32_e32 v116, v115, v99
	v_fma_f32 v117, v114, v107, v116
	v_cvt_pk_bf16_f32 v186, v119, v117
	v_lshlrev_b32_e32 v114, 16, v183
	v_lshlrev_b32_e32 v115, 16, v187
	v_mul_f32_e32 v116, v115, v108
	v_fma_f32 v118, v114, v100, -v116
	v_mul_f32_e32 v116, v115, v100
	v_fma_f32 v119, v114, v108, v116
	v_and_b32_e32 v114, 0xffff0000, v183
	v_and_b32_e32 v115, 0xffff0000, v187
	v_mul_f32_e32 v116, v115, v109
	v_fma_f32 v117, v114, v101, -v116
	v_cvt_pk_bf16_f32 v183, v118, v117
	v_mul_f32_e32 v116, v115, v101
	v_fma_f32 v117, v114, v109, v116
	v_cvt_pk_bf16_f32 v187, v119, v117
	v_lshlrev_b32_e32 v114, 16, v184
	v_lshlrev_b32_e32 v115, 16, v188
	v_mul_f32_e32 v116, v115, v110
	v_fma_f32 v118, v114, v102, -v116
	v_mul_f32_e32 v116, v115, v102
	v_fma_f32 v119, v114, v110, v116
	v_and_b32_e32 v114, 0xffff0000, v184
	v_and_b32_e32 v115, 0xffff0000, v188
	v_mul_f32_e32 v116, v115, v111
	v_fma_f32 v117, v114, v103, -v116
	v_cvt_pk_bf16_f32 v184, v118, v117
	v_mul_f32_e32 v116, v115, v103
	v_fma_f32 v117, v114, v111, v116
	v_cvt_pk_bf16_f32 v188, v119, v117
	v_lshlrev_b32_e32 v114, 16, v185
	v_lshlrev_b32_e32 v115, 16, v189
	v_mul_f32_e32 v116, v115, v112
	v_fma_f32 v118, v114, v104, -v116
	v_mul_f32_e32 v116, v115, v104
	v_fma_f32 v119, v114, v112, v116
	v_and_b32_e32 v114, 0xffff0000, v185
	v_and_b32_e32 v115, 0xffff0000, v189
	v_mul_f32_e32 v116, v115, v113
	v_fma_f32 v117, v114, v105, -v116
	v_cvt_pk_bf16_f32 v185, v118, v117
	v_mul_f32_e32 v116, v115, v105
	v_fma_f32 v117, v114, v113, v116
	v_cvt_pk_bf16_f32 v189, v119, v117
	s_waitcnt lgkmcnt(0)
	s_barrier
	s_nop 0
